# diff_rows batched with 16 consecutive rows per wave instead of rows strided by the wave count
# baseline (speedup 1.0000x reference)
.LBB0_398:
	v_and_b32_e32 v10, 15, v246
	v_lshrrev_b32_e32 v11, 4, v246
	v_lshlrev_b32_e32 v10, 4, v10
	s_lshl_b32 s4, s46, 15
	v_lshl_add_u32 v12, v11, 9, v10
	v_lshl_add_u32 v13, v11, 8, v10
	s_add_u32 s24, s50, s4
	s_addc_u32 s25, s51, 0
	s_add_u32 s14, s54, s4
	s_addc_u32 s15, s55, 0
	global_load_dwordx4 v[100:103], v12, s[24:25]
	global_load_dwordx4 v[104:107], v12, s[24:25] offset:256
	s_add_u32 s24, s24, 0x800
	s_addc_u32 s25, s25, 0
	global_load_dwordx4 v[108:111], v12, s[24:25]
	global_load_dwordx4 v[112:115], v12, s[24:25] offset:256
	s_add_u32 s24, s24, 0x800
	s_addc_u32 s25, s25, 0
	global_load_dwordx4 v[116:119], v12, s[24:25]
	global_load_dwordx4 v[120:123], v12, s[24:25] offset:256
	s_add_u32 s24, s24, 0x800
	s_addc_u32 s25, s25, 0
	global_load_dwordx4 v[124:127], v12, s[24:25]
	global_load_dwordx4 v[128:131], v12, s[24:25] offset:256
	s_add_u32 s24, s24, 0x800
	s_addc_u32 s25, s25, 0
	global_load_dwordx4 v[132:135], v12, s[24:25]
	global_load_dwordx4 v[136:139], v12, s[24:25] offset:256
	s_add_u32 s24, s24, 0x800
	s_addc_u32 s25, s25, 0
	global_load_dwordx4 v[140:143], v12, s[24:25]
	global_load_dwordx4 v[144:147], v12, s[24:25] offset:256
	s_add_u32 s24, s24, 0x800
	s_addc_u32 s25, s25, 0
	global_load_dwordx4 v[148:151], v12, s[24:25]
	global_load_dwordx4 v[152:155], v12, s[24:25] offset:256
	s_add_u32 s24, s24, 0x800
	s_addc_u32 s25, s25, 0
	global_load_dwordx4 v[156:159], v12, s[24:25]
	global_load_dwordx4 v[160:163], v12, s[24:25] offset:256
	s_add_u32 s24, s24, 0x800
	s_addc_u32 s25, s25, 0
	global_load_dwordx4 v[164:167], v12, s[24:25]
	global_load_dwordx4 v[168:171], v12, s[24:25] offset:256
	s_add_u32 s24, s24, 0x800
	s_addc_u32 s25, s25, 0
	global_load_dwordx4 v[172:175], v12, s[24:25]
	global_load_dwordx4 v[176:179], v12, s[24:25] offset:256
	s_add_u32 s24, s24, 0x800
	s_addc_u32 s25, s25, 0
	global_load_dwordx4 v[180:183], v12, s[24:25]
	global_load_dwordx4 v[184:187], v12, s[24:25] offset:256
	s_add_u32 s24, s24, 0x800
	s_addc_u32 s25, s25, 0
	global_load_dwordx4 v[188:191], v12, s[24:25]
	global_load_dwordx4 v[192:195], v12, s[24:25] offset:256
	s_add_u32 s24, s24, 0x800
	s_addc_u32 s25, s25, 0
	global_load_dwordx4 v[196:199], v12, s[24:25]
	global_load_dwordx4 v[200:203], v12, s[24:25] offset:256
	s_add_u32 s24, s24, 0x800
	s_addc_u32 s25, s25, 0
	global_load_dwordx4 v[204:207], v12, s[24:25]
	global_load_dwordx4 v[208:211], v12, s[24:25] offset:256
	s_add_u32 s24, s24, 0x800
	s_addc_u32 s25, s25, 0
	global_load_dwordx4 v[212:215], v12, s[24:25]
	global_load_dwordx4 v[216:219], v12, s[24:25] offset:256
	s_add_u32 s24, s24, 0x800
	s_addc_u32 s25, s25, 0
	global_load_dwordx4 v[220:223], v12, s[24:25]
	global_load_dwordx4 v[224:227], v12, s[24:25] offset:256
	s_waitcnt vmcnt(30) lgkmcnt(0)
	v_lshlrev_b32_e32 v54, 16, v104
	v_and_b32_e32 v55, 0xffff0000, v104
	v_lshlrev_b32_e32 v56, 16, v105
	v_and_b32_e32 v57, 0xffff0000, v105
	v_lshlrev_b32_e32 v58, 16, v106
	v_and_b32_e32 v59, 0xffff0000, v106
	v_lshlrev_b32_e32 v60, 16, v107
	v_and_b32_e32 v61, 0xffff0000, v107
	v_lshlrev_b32_e32 v106, 16, v103
	v_and_b32_e32 v107, 0xffff0000, v103
	v_lshlrev_b32_e32 v104, 16, v102
	v_and_b32_e32 v105, 0xffff0000, v102
	v_and_b32_e32 v103, 0xffff0000, v101
	v_lshlrev_b32_e32 v102, 16, v101
	v_and_b32_e32 v101, 0xffff0000, v100
	v_lshlrev_b32_e32 v100, 16, v100
	v_pk_fma_f32 v[100:101], v[42:43], v[54:55], v[100:101] neg_lo:[1,0,0] neg_hi:[1,0,0]
	v_pk_fma_f32 v[102:103], v[42:43], v[56:57], v[102:103] neg_lo:[1,0,0] neg_hi:[1,0,0]
	v_pk_fma_f32 v[104:105], v[42:43], v[58:59], v[104:105] neg_lo:[1,0,0] neg_hi:[1,0,0]
	v_pk_fma_f32 v[106:107], v[42:43], v[60:61], v[106:107] neg_lo:[1,0,0] neg_hi:[1,0,0]
	v_mul_f32_e32 v54, v101, v101
	v_mul_f32_e32 v55, v103, v103
	v_mul_f32_e32 v56, v105, v105
	v_mul_f32_e32 v57, v107, v107
	v_fma_f32 v54, v100, v100, v54
	v_fma_f32 v55, v102, v102, v55
	v_fma_f32 v56, v104, v104, v56
	v_fma_f32 v57, v106, v106, v57
	v_add_f32_e32 v54, v54, v55
	v_add_f32_e32 v56, v56, v57
	v_add_f32_e32 v62, v54, v56
	s_waitcnt vmcnt(28)
	v_lshlrev_b32_e32 v54, 16, v112
	v_and_b32_e32 v55, 0xffff0000, v112
	v_lshlrev_b32_e32 v56, 16, v113
	v_and_b32_e32 v57, 0xffff0000, v113
	v_lshlrev_b32_e32 v58, 16, v114
	v_and_b32_e32 v59, 0xffff0000, v114
	v_lshlrev_b32_e32 v60, 16, v115
	v_and_b32_e32 v61, 0xffff0000, v115
	v_lshlrev_b32_e32 v114, 16, v111
	v_and_b32_e32 v115, 0xffff0000, v111
	v_lshlrev_b32_e32 v112, 16, v110
	v_and_b32_e32 v113, 0xffff0000, v110
	v_and_b32_e32 v111, 0xffff0000, v109
	v_lshlrev_b32_e32 v110, 16, v109
	v_and_b32_e32 v109, 0xffff0000, v108
	v_lshlrev_b32_e32 v108, 16, v108
	v_pk_fma_f32 v[108:109], v[42:43], v[54:55], v[108:109] neg_lo:[1,0,0] neg_hi:[1,0,0]
	v_pk_fma_f32 v[110:111], v[42:43], v[56:57], v[110:111] neg_lo:[1,0,0] neg_hi:[1,0,0]
	v_pk_fma_f32 v[112:113], v[42:43], v[58:59], v[112:113] neg_lo:[1,0,0] neg_hi:[1,0,0]
	v_pk_fma_f32 v[114:115], v[42:43], v[60:61], v[114:115] neg_lo:[1,0,0] neg_hi:[1,0,0]
	v_mul_f32_e32 v54, v109, v109
	v_mul_f32_e32 v55, v111, v111
	v_mul_f32_e32 v56, v113, v113
	v_mul_f32_e32 v57, v115, v115
	v_fma_f32 v54, v108, v108, v54
	v_fma_f32 v55, v110, v110, v55
	v_fma_f32 v56, v112, v112, v56
	v_fma_f32 v57, v114, v114, v57
	v_add_f32_e32 v54, v54, v55
	v_add_f32_e32 v56, v56, v57
	v_add_f32_e32 v63, v54, v56
	s_waitcnt vmcnt(26)
	v_lshlrev_b32_e32 v54, 16, v120
	v_and_b32_e32 v55, 0xffff0000, v120
	v_lshlrev_b32_e32 v56, 16, v121
	v_and_b32_e32 v57, 0xffff0000, v121
	v_lshlrev_b32_e32 v58, 16, v122
	v_and_b32_e32 v59, 0xffff0000, v122
	v_lshlrev_b32_e32 v60, 16, v123
	v_and_b32_e32 v61, 0xffff0000, v123
	v_lshlrev_b32_e32 v122, 16, v119
	v_and_b32_e32 v123, 0xffff0000, v119
	v_lshlrev_b32_e32 v120, 16, v118
	v_and_b32_e32 v121, 0xffff0000, v118
	v_and_b32_e32 v119, 0xffff0000, v117
	v_lshlrev_b32_e32 v118, 16, v117
	v_and_b32_e32 v117, 0xffff0000, v116
	v_lshlrev_b32_e32 v116, 16, v116
	v_pk_fma_f32 v[116:117], v[42:43], v[54:55], v[116:117] neg_lo:[1,0,0] neg_hi:[1,0,0]
	v_pk_fma_f32 v[118:119], v[42:43], v[56:57], v[118:119] neg_lo:[1,0,0] neg_hi:[1,0,0]
	v_pk_fma_f32 v[120:121], v[42:43], v[58:59], v[120:121] neg_lo:[1,0,0] neg_hi:[1,0,0]
	v_pk_fma_f32 v[122:123], v[42:43], v[60:61], v[122:123] neg_lo:[1,0,0] neg_hi:[1,0,0]
	v_mul_f32_e32 v54, v117, v117
	v_mul_f32_e32 v55, v119, v119
	v_mul_f32_e32 v56, v121, v121
	v_mul_f32_e32 v57, v123, v123
	v_fma_f32 v54, v116, v116, v54
	v_fma_f32 v55, v118, v118, v55
	v_fma_f32 v56, v120, v120, v56
	v_fma_f32 v57, v122, v122, v57
	v_add_f32_e32 v54, v54, v55
	v_add_f32_e32 v56, v56, v57
	v_add_f32_e32 v64, v54, v56
	s_waitcnt vmcnt(24)
	v_lshlrev_b32_e32 v54, 16, v128
	v_and_b32_e32 v55, 0xffff0000, v128
	v_lshlrev_b32_e32 v56, 16, v129
	v_and_b32_e32 v57, 0xffff0000, v129
	v_lshlrev_b32_e32 v58, 16, v130
	v_and_b32_e32 v59, 0xffff0000, v130
	v_lshlrev_b32_e32 v60, 16, v131
	v_and_b32_e32 v61, 0xffff0000, v131
	v_lshlrev_b32_e32 v130, 16, v127
	v_and_b32_e32 v131, 0xffff0000, v127
	v_lshlrev_b32_e32 v128, 16, v126
	v_and_b32_e32 v129, 0xffff0000, v126
	v_and_b32_e32 v127, 0xffff0000, v125
	v_lshlrev_b32_e32 v126, 16, v125
	v_and_b32_e32 v125, 0xffff0000, v124
	v_lshlrev_b32_e32 v124, 16, v124
	v_pk_fma_f32 v[124:125], v[42:43], v[54:55], v[124:125] neg_lo:[1,0,0] neg_hi:[1,0,0]
	v_pk_fma_f32 v[126:127], v[42:43], v[56:57], v[126:127] neg_lo:[1,0,0] neg_hi:[1,0,0]
	v_pk_fma_f32 v[128:129], v[42:43], v[58:59], v[128:129] neg_lo:[1,0,0] neg_hi:[1,0,0]
	v_pk_fma_f32 v[130:131], v[42:43], v[60:61], v[130:131] neg_lo:[1,0,0] neg_hi:[1,0,0]
	v_mul_f32_e32 v54, v125, v125
	v_mul_f32_e32 v55, v127, v127
	v_mul_f32_e32 v56, v129, v129
	v_mul_f32_e32 v57, v131, v131
	v_fma_f32 v54, v124, v124, v54
	v_fma_f32 v55, v126, v126, v55
	v_fma_f32 v56, v128, v128, v56
	v_fma_f32 v57, v130, v130, v57
	v_add_f32_e32 v54, v54, v55
	v_add_f32_e32 v56, v56, v57
	v_add_f32_e32 v65, v54, v56
	s_waitcnt vmcnt(22)
	v_lshlrev_b32_e32 v54, 16, v136
	v_and_b32_e32 v55, 0xffff0000, v136
	v_lshlrev_b32_e32 v56, 16, v137
	v_and_b32_e32 v57, 0xffff0000, v137
	v_lshlrev_b32_e32 v58, 16, v138
	v_and_b32_e32 v59, 0xffff0000, v138
	v_lshlrev_b32_e32 v60, 16, v139
	v_and_b32_e32 v61, 0xffff0000, v139
	v_lshlrev_b32_e32 v138, 16, v135
	v_and_b32_e32 v139, 0xffff0000, v135
	v_lshlrev_b32_e32 v136, 16, v134
	v_and_b32_e32 v137, 0xffff0000, v134
	v_and_b32_e32 v135, 0xffff0000, v133
	v_lshlrev_b32_e32 v134, 16, v133
	v_and_b32_e32 v133, 0xffff0000, v132
	v_lshlrev_b32_e32 v132, 16, v132
	v_pk_fma_f32 v[132:133], v[42:43], v[54:55], v[132:133] neg_lo:[1,0,0] neg_hi:[1,0,0]
	v_pk_fma_f32 v[134:135], v[42:43], v[56:57], v[134:135] neg_lo:[1,0,0] neg_hi:[1,0,0]
	v_pk_fma_f32 v[136:137], v[42:43], v[58:59], v[136:137] neg_lo:[1,0,0] neg_hi:[1,0,0]
	v_pk_fma_f32 v[138:139], v[42:43], v[60:61], v[138:139] neg_lo:[1,0,0] neg_hi:[1,0,0]
	v_mul_f32_e32 v54, v133, v133
	v_mul_f32_e32 v55, v135, v135
	v_mul_f32_e32 v56, v137, v137
	v_mul_f32_e32 v57, v139, v139
	v_fma_f32 v54, v132, v132, v54
	v_fma_f32 v55, v134, v134, v55
	v_fma_f32 v56, v136, v136, v56
	v_fma_f32 v57, v138, v138, v57
	v_add_f32_e32 v54, v54, v55
	v_add_f32_e32 v56, v56, v57
	v_add_f32_e32 v66, v54, v56
	s_waitcnt vmcnt(20)
	v_lshlrev_b32_e32 v54, 16, v144
	v_and_b32_e32 v55, 0xffff0000, v144
	v_lshlrev_b32_e32 v56, 16, v145
	v_and_b32_e32 v57, 0xffff0000, v145
	v_lshlrev_b32_e32 v58, 16, v146
	v_and_b32_e32 v59, 0xffff0000, v146
	v_lshlrev_b32_e32 v60, 16, v147
	v_and_b32_e32 v61, 0xffff0000, v147
	v_lshlrev_b32_e32 v146, 16, v143
	v_and_b32_e32 v147, 0xffff0000, v143
	v_lshlrev_b32_e32 v144, 16, v142
	v_and_b32_e32 v145, 0xffff0000, v142
	v_and_b32_e32 v143, 0xffff0000, v141
	v_lshlrev_b32_e32 v142, 16, v141
	v_and_b32_e32 v141, 0xffff0000, v140
	v_lshlrev_b32_e32 v140, 16, v140
	v_pk_fma_f32 v[140:141], v[42:43], v[54:55], v[140:141] neg_lo:[1,0,0] neg_hi:[1,0,0]
	v_pk_fma_f32 v[142:143], v[42:43], v[56:57], v[142:143] neg_lo:[1,0,0] neg_hi:[1,0,0]
	v_pk_fma_f32 v[144:145], v[42:43], v[58:59], v[144:145] neg_lo:[1,0,0] neg_hi:[1,0,0]
	v_pk_fma_f32 v[146:147], v[42:43], v[60:61], v[146:147] neg_lo:[1,0,0] neg_hi:[1,0,0]
	v_mul_f32_e32 v54, v141, v141
	v_mul_f32_e32 v55, v143, v143
	v_mul_f32_e32 v56, v145, v145
	v_mul_f32_e32 v57, v147, v147
	v_fma_f32 v54, v140, v140, v54
	v_fma_f32 v55, v142, v142, v55
	v_fma_f32 v56, v144, v144, v56
	v_fma_f32 v57, v146, v146, v57
	v_add_f32_e32 v54, v54, v55
	v_add_f32_e32 v56, v56, v57
	v_add_f32_e32 v67, v54, v56
	s_waitcnt vmcnt(18)
	v_lshlrev_b32_e32 v54, 16, v152
	v_and_b32_e32 v55, 0xffff0000, v152
	v_lshlrev_b32_e32 v56, 16, v153
	v_and_b32_e32 v57, 0xffff0000, v153
	v_lshlrev_b32_e32 v58, 16, v154
	v_and_b32_e32 v59, 0xffff0000, v154
	v_lshlrev_b32_e32 v60, 16, v155
	v_and_b32_e32 v61, 0xffff0000, v155
	v_lshlrev_b32_e32 v154, 16, v151
	v_and_b32_e32 v155, 0xffff0000, v151
	v_lshlrev_b32_e32 v152, 16, v150
	v_and_b32_e32 v153, 0xffff0000, v150
	v_and_b32_e32 v151, 0xffff0000, v149
	v_lshlrev_b32_e32 v150, 16, v149
	v_and_b32_e32 v149, 0xffff0000, v148
	v_lshlrev_b32_e32 v148, 16, v148
	v_pk_fma_f32 v[148:149], v[42:43], v[54:55], v[148:149] neg_lo:[1,0,0] neg_hi:[1,0,0]
	v_pk_fma_f32 v[150:151], v[42:43], v[56:57], v[150:151] neg_lo:[1,0,0] neg_hi:[1,0,0]
	v_pk_fma_f32 v[152:153], v[42:43], v[58:59], v[152:153] neg_lo:[1,0,0] neg_hi:[1,0,0]
	v_pk_fma_f32 v[154:155], v[42:43], v[60:61], v[154:155] neg_lo:[1,0,0] neg_hi:[1,0,0]
	v_mul_f32_e32 v54, v149, v149
	v_mul_f32_e32 v55, v151, v151
	v_mul_f32_e32 v56, v153, v153
	v_mul_f32_e32 v57, v155, v155
	v_fma_f32 v54, v148, v148, v54
	v_fma_f32 v55, v150, v150, v55
	v_fma_f32 v56, v152, v152, v56
	v_fma_f32 v57, v154, v154, v57
	v_add_f32_e32 v54, v54, v55
	v_add_f32_e32 v56, v56, v57
	v_add_f32_e32 v68, v54, v56
	s_waitcnt vmcnt(16)
	v_lshlrev_b32_e32 v54, 16, v160
	v_and_b32_e32 v55, 0xffff0000, v160
	v_lshlrev_b32_e32 v56, 16, v161
	v_and_b32_e32 v57, 0xffff0000, v161
	v_lshlrev_b32_e32 v58, 16, v162
	v_and_b32_e32 v59, 0xffff0000, v162
	v_lshlrev_b32_e32 v60, 16, v163
	v_and_b32_e32 v61, 0xffff0000, v163
	v_lshlrev_b32_e32 v162, 16, v159
	v_and_b32_e32 v163, 0xffff0000, v159
	v_lshlrev_b32_e32 v160, 16, v158
	v_and_b32_e32 v161, 0xffff0000, v158
	v_and_b32_e32 v159, 0xffff0000, v157
	v_lshlrev_b32_e32 v158, 16, v157
	v_and_b32_e32 v157, 0xffff0000, v156
	v_lshlrev_b32_e32 v156, 16, v156
	v_pk_fma_f32 v[156:157], v[42:43], v[54:55], v[156:157] neg_lo:[1,0,0] neg_hi:[1,0,0]
	v_pk_fma_f32 v[158:159], v[42:43], v[56:57], v[158:159] neg_lo:[1,0,0] neg_hi:[1,0,0]
	v_pk_fma_f32 v[160:161], v[42:43], v[58:59], v[160:161] neg_lo:[1,0,0] neg_hi:[1,0,0]
	v_pk_fma_f32 v[162:163], v[42:43], v[60:61], v[162:163] neg_lo:[1,0,0] neg_hi:[1,0,0]
	v_mul_f32_e32 v54, v157, v157
	v_mul_f32_e32 v55, v159, v159
	v_mul_f32_e32 v56, v161, v161
	v_mul_f32_e32 v57, v163, v163
	v_fma_f32 v54, v156, v156, v54
	v_fma_f32 v55, v158, v158, v55
	v_fma_f32 v56, v160, v160, v56
	v_fma_f32 v57, v162, v162, v57
	v_add_f32_e32 v54, v54, v55
	v_add_f32_e32 v56, v56, v57
	v_add_f32_e32 v69, v54, v56
	s_waitcnt vmcnt(14)
	v_lshlrev_b32_e32 v54, 16, v168
	v_and_b32_e32 v55, 0xffff0000, v168
	v_lshlrev_b32_e32 v56, 16, v169
	v_and_b32_e32 v57, 0xffff0000, v169
	v_lshlrev_b32_e32 v58, 16, v170
	v_and_b32_e32 v59, 0xffff0000, v170
	v_lshlrev_b32_e32 v60, 16, v171
	v_and_b32_e32 v61, 0xffff0000, v171
	v_lshlrev_b32_e32 v170, 16, v167
	v_and_b32_e32 v171, 0xffff0000, v167
	v_lshlrev_b32_e32 v168, 16, v166
	v_and_b32_e32 v169, 0xffff0000, v166
	v_and_b32_e32 v167, 0xffff0000, v165
	v_lshlrev_b32_e32 v166, 16, v165
	v_and_b32_e32 v165, 0xffff0000, v164
	v_lshlrev_b32_e32 v164, 16, v164
	v_pk_fma_f32 v[164:165], v[42:43], v[54:55], v[164:165] neg_lo:[1,0,0] neg_hi:[1,0,0]
	v_pk_fma_f32 v[166:167], v[42:43], v[56:57], v[166:167] neg_lo:[1,0,0] neg_hi:[1,0,0]
	v_pk_fma_f32 v[168:169], v[42:43], v[58:59], v[168:169] neg_lo:[1,0,0] neg_hi:[1,0,0]
	v_pk_fma_f32 v[170:171], v[42:43], v[60:61], v[170:171] neg_lo:[1,0,0] neg_hi:[1,0,0]
	v_mul_f32_e32 v54, v165, v165
	v_mul_f32_e32 v55, v167, v167
	v_mul_f32_e32 v56, v169, v169
	v_mul_f32_e32 v57, v171, v171
	v_fma_f32 v54, v164, v164, v54
	v_fma_f32 v55, v166, v166, v55
	v_fma_f32 v56, v168, v168, v56
	v_fma_f32 v57, v170, v170, v57
	v_add_f32_e32 v54, v54, v55
	v_add_f32_e32 v56, v56, v57
	v_add_f32_e32 v70, v54, v56
	s_waitcnt vmcnt(12)
	v_lshlrev_b32_e32 v54, 16, v176
	v_and_b32_e32 v55, 0xffff0000, v176
	v_lshlrev_b32_e32 v56, 16, v177
	v_and_b32_e32 v57, 0xffff0000, v177
	v_lshlrev_b32_e32 v58, 16, v178
	v_and_b32_e32 v59, 0xffff0000, v178
	v_lshlrev_b32_e32 v60, 16, v179
	v_and_b32_e32 v61, 0xffff0000, v179
	v_lshlrev_b32_e32 v178, 16, v175
	v_and_b32_e32 v179, 0xffff0000, v175
	v_lshlrev_b32_e32 v176, 16, v174
	v_and_b32_e32 v177, 0xffff0000, v174
	v_and_b32_e32 v175, 0xffff0000, v173
	v_lshlrev_b32_e32 v174, 16, v173
	v_and_b32_e32 v173, 0xffff0000, v172
	v_lshlrev_b32_e32 v172, 16, v172
	v_pk_fma_f32 v[172:173], v[42:43], v[54:55], v[172:173] neg_lo:[1,0,0] neg_hi:[1,0,0]
	v_pk_fma_f32 v[174:175], v[42:43], v[56:57], v[174:175] neg_lo:[1,0,0] neg_hi:[1,0,0]
	v_pk_fma_f32 v[176:177], v[42:43], v[58:59], v[176:177] neg_lo:[1,0,0] neg_hi:[1,0,0]
	v_pk_fma_f32 v[178:179], v[42:43], v[60:61], v[178:179] neg_lo:[1,0,0] neg_hi:[1,0,0]
	v_mul_f32_e32 v54, v173, v173
	v_mul_f32_e32 v55, v175, v175
	v_mul_f32_e32 v56, v177, v177
	v_mul_f32_e32 v57, v179, v179
	v_fma_f32 v54, v172, v172, v54
	v_fma_f32 v55, v174, v174, v55
	v_fma_f32 v56, v176, v176, v56
	v_fma_f32 v57, v178, v178, v57
	v_add_f32_e32 v54, v54, v55
	v_add_f32_e32 v56, v56, v57
	v_add_f32_e32 v71, v54, v56
	s_waitcnt vmcnt(10)
	v_lshlrev_b32_e32 v54, 16, v184
	v_and_b32_e32 v55, 0xffff0000, v184
	v_lshlrev_b32_e32 v56, 16, v185
	v_and_b32_e32 v57, 0xffff0000, v185
	v_lshlrev_b32_e32 v58, 16, v186
	v_and_b32_e32 v59, 0xffff0000, v186
	v_lshlrev_b32_e32 v60, 16, v187
	v_and_b32_e32 v61, 0xffff0000, v187
	v_lshlrev_b32_e32 v186, 16, v183
	v_and_b32_e32 v187, 0xffff0000, v183
	v_lshlrev_b32_e32 v184, 16, v182
	v_and_b32_e32 v185, 0xffff0000, v182
	v_and_b32_e32 v183, 0xffff0000, v181
	v_lshlrev_b32_e32 v182, 16, v181
	v_and_b32_e32 v181, 0xffff0000, v180
	v_lshlrev_b32_e32 v180, 16, v180
	v_pk_fma_f32 v[180:181], v[42:43], v[54:55], v[180:181] neg_lo:[1,0,0] neg_hi:[1,0,0]
	v_pk_fma_f32 v[182:183], v[42:43], v[56:57], v[182:183] neg_lo:[1,0,0] neg_hi:[1,0,0]
	v_pk_fma_f32 v[184:185], v[42:43], v[58:59], v[184:185] neg_lo:[1,0,0] neg_hi:[1,0,0]
	v_pk_fma_f32 v[186:187], v[42:43], v[60:61], v[186:187] neg_lo:[1,0,0] neg_hi:[1,0,0]
	v_mul_f32_e32 v54, v181, v181
	v_mul_f32_e32 v55, v183, v183
	v_mul_f32_e32 v56, v185, v185
	v_mul_f32_e32 v57, v187, v187
	v_fma_f32 v54, v180, v180, v54
	v_fma_f32 v55, v182, v182, v55
	v_fma_f32 v56, v184, v184, v56
	v_fma_f32 v57, v186, v186, v57
	v_add_f32_e32 v54, v54, v55
	v_add_f32_e32 v56, v56, v57
	v_add_f32_e32 v72, v54, v56
	s_waitcnt vmcnt(8)
	v_lshlrev_b32_e32 v54, 16, v192
	v_and_b32_e32 v55, 0xffff0000, v192
	v_lshlrev_b32_e32 v56, 16, v193
	v_and_b32_e32 v57, 0xffff0000, v193
	v_lshlrev_b32_e32 v58, 16, v194
	v_and_b32_e32 v59, 0xffff0000, v194
	v_lshlrev_b32_e32 v60, 16, v195
	v_and_b32_e32 v61, 0xffff0000, v195
	v_lshlrev_b32_e32 v194, 16, v191
	v_and_b32_e32 v195, 0xffff0000, v191
	v_lshlrev_b32_e32 v192, 16, v190
	v_and_b32_e32 v193, 0xffff0000, v190
	v_and_b32_e32 v191, 0xffff0000, v189
	v_lshlrev_b32_e32 v190, 16, v189
	v_and_b32_e32 v189, 0xffff0000, v188
	v_lshlrev_b32_e32 v188, 16, v188
	v_pk_fma_f32 v[188:189], v[42:43], v[54:55], v[188:189] neg_lo:[1,0,0] neg_hi:[1,0,0]
	v_pk_fma_f32 v[190:191], v[42:43], v[56:57], v[190:191] neg_lo:[1,0,0] neg_hi:[1,0,0]
	v_pk_fma_f32 v[192:193], v[42:43], v[58:59], v[192:193] neg_lo:[1,0,0] neg_hi:[1,0,0]
	v_pk_fma_f32 v[194:195], v[42:43], v[60:61], v[194:195] neg_lo:[1,0,0] neg_hi:[1,0,0]
	v_mul_f32_e32 v54, v189, v189
	v_mul_f32_e32 v55, v191, v191
	v_mul_f32_e32 v56, v193, v193
	v_mul_f32_e32 v57, v195, v195
	v_fma_f32 v54, v188, v188, v54
	v_fma_f32 v55, v190, v190, v55
	v_fma_f32 v56, v192, v192, v56
	v_fma_f32 v57, v194, v194, v57
	v_add_f32_e32 v54, v54, v55
	v_add_f32_e32 v56, v56, v57
	v_add_f32_e32 v73, v54, v56
	s_waitcnt vmcnt(6)
	v_lshlrev_b32_e32 v54, 16, v200
	v_and_b32_e32 v55, 0xffff0000, v200
	v_lshlrev_b32_e32 v56, 16, v201
	v_and_b32_e32 v57, 0xffff0000, v201
	v_lshlrev_b32_e32 v58, 16, v202
	v_and_b32_e32 v59, 0xffff0000, v202
	v_lshlrev_b32_e32 v60, 16, v203
	v_and_b32_e32 v61, 0xffff0000, v203
	v_lshlrev_b32_e32 v202, 16, v199
	v_and_b32_e32 v203, 0xffff0000, v199
	v_lshlrev_b32_e32 v200, 16, v198
	v_and_b32_e32 v201, 0xffff0000, v198
	v_and_b32_e32 v199, 0xffff0000, v197
	v_lshlrev_b32_e32 v198, 16, v197
	v_and_b32_e32 v197, 0xffff0000, v196
	v_lshlrev_b32_e32 v196, 16, v196
	v_pk_fma_f32 v[196:197], v[42:43], v[54:55], v[196:197] neg_lo:[1,0,0] neg_hi:[1,0,0]
	v_pk_fma_f32 v[198:199], v[42:43], v[56:57], v[198:199] neg_lo:[1,0,0] neg_hi:[1,0,0]
	v_pk_fma_f32 v[200:201], v[42:43], v[58:59], v[200:201] neg_lo:[1,0,0] neg_hi:[1,0,0]
	v_pk_fma_f32 v[202:203], v[42:43], v[60:61], v[202:203] neg_lo:[1,0,0] neg_hi:[1,0,0]
	v_mul_f32_e32 v54, v197, v197
	v_mul_f32_e32 v55, v199, v199
	v_mul_f32_e32 v56, v201, v201
	v_mul_f32_e32 v57, v203, v203
	v_fma_f32 v54, v196, v196, v54
	v_fma_f32 v55, v198, v198, v55
	v_fma_f32 v56, v200, v200, v56
	v_fma_f32 v57, v202, v202, v57
	v_add_f32_e32 v54, v54, v55
	v_add_f32_e32 v56, v56, v57
	v_add_f32_e32 v74, v54, v56
	s_waitcnt vmcnt(4)
	v_lshlrev_b32_e32 v54, 16, v208
	v_and_b32_e32 v55, 0xffff0000, v208
	v_lshlrev_b32_e32 v56, 16, v209
	v_and_b32_e32 v57, 0xffff0000, v209
	v_lshlrev_b32_e32 v58, 16, v210
	v_and_b32_e32 v59, 0xffff0000, v210
	v_lshlrev_b32_e32 v60, 16, v211
	v_and_b32_e32 v61, 0xffff0000, v211
	v_lshlrev_b32_e32 v210, 16, v207
	v_and_b32_e32 v211, 0xffff0000, v207
	v_lshlrev_b32_e32 v208, 16, v206
	v_and_b32_e32 v209, 0xffff0000, v206
	v_and_b32_e32 v207, 0xffff0000, v205
	v_lshlrev_b32_e32 v206, 16, v205
	v_and_b32_e32 v205, 0xffff0000, v204
	v_lshlrev_b32_e32 v204, 16, v204
	v_pk_fma_f32 v[204:205], v[42:43], v[54:55], v[204:205] neg_lo:[1,0,0] neg_hi:[1,0,0]
	v_pk_fma_f32 v[206:207], v[42:43], v[56:57], v[206:207] neg_lo:[1,0,0] neg_hi:[1,0,0]
	v_pk_fma_f32 v[208:209], v[42:43], v[58:59], v[208:209] neg_lo:[1,0,0] neg_hi:[1,0,0]
	v_pk_fma_f32 v[210:211], v[42:43], v[60:61], v[210:211] neg_lo:[1,0,0] neg_hi:[1,0,0]
	v_mul_f32_e32 v54, v205, v205
	v_mul_f32_e32 v55, v207, v207
	v_mul_f32_e32 v56, v209, v209
	v_mul_f32_e32 v57, v211, v211
	v_fma_f32 v54, v204, v204, v54
	v_fma_f32 v55, v206, v206, v55
	v_fma_f32 v56, v208, v208, v56
	v_fma_f32 v57, v210, v210, v57
	v_add_f32_e32 v54, v54, v55
	v_add_f32_e32 v56, v56, v57
	v_add_f32_e32 v75, v54, v56
	s_waitcnt vmcnt(2)
	v_lshlrev_b32_e32 v54, 16, v216
	v_and_b32_e32 v55, 0xffff0000, v216
	v_lshlrev_b32_e32 v56, 16, v217
	v_and_b32_e32 v57, 0xffff0000, v217
	v_lshlrev_b32_e32 v58, 16, v218
	v_and_b32_e32 v59, 0xffff0000, v218
	v_lshlrev_b32_e32 v60, 16, v219
	v_and_b32_e32 v61, 0xffff0000, v219
	v_lshlrev_b32_e32 v218, 16, v215
	v_and_b32_e32 v219, 0xffff0000, v215
	v_lshlrev_b32_e32 v216, 16, v214
	v_and_b32_e32 v217, 0xffff0000, v214
	v_and_b32_e32 v215, 0xffff0000, v213
	v_lshlrev_b32_e32 v214, 16, v213
	v_and_b32_e32 v213, 0xffff0000, v212
	v_lshlrev_b32_e32 v212, 16, v212
	v_pk_fma_f32 v[212:213], v[42:43], v[54:55], v[212:213] neg_lo:[1,0,0] neg_hi:[1,0,0]
	v_pk_fma_f32 v[214:215], v[42:43], v[56:57], v[214:215] neg_lo:[1,0,0] neg_hi:[1,0,0]
	v_pk_fma_f32 v[216:217], v[42:43], v[58:59], v[216:217] neg_lo:[1,0,0] neg_hi:[1,0,0]
	v_pk_fma_f32 v[218:219], v[42:43], v[60:61], v[218:219] neg_lo:[1,0,0] neg_hi:[1,0,0]
	v_mul_f32_e32 v54, v213, v213
	v_mul_f32_e32 v55, v215, v215
	v_mul_f32_e32 v56, v217, v217
	v_mul_f32_e32 v57, v219, v219
	v_fma_f32 v54, v212, v212, v54
	v_fma_f32 v55, v214, v214, v55
	v_fma_f32 v56, v216, v216, v56
	v_fma_f32 v57, v218, v218, v57
	v_add_f32_e32 v54, v54, v55
	v_add_f32_e32 v56, v56, v57
	v_add_f32_e32 v76, v54, v56
	s_waitcnt vmcnt(0)
	v_lshlrev_b32_e32 v54, 16, v224
	v_and_b32_e32 v55, 0xffff0000, v224
	v_lshlrev_b32_e32 v56, 16, v225
	v_and_b32_e32 v57, 0xffff0000, v225
	v_lshlrev_b32_e32 v58, 16, v226
	v_and_b32_e32 v59, 0xffff0000, v226
	v_lshlrev_b32_e32 v60, 16, v227
	v_and_b32_e32 v61, 0xffff0000, v227
	v_lshlrev_b32_e32 v226, 16, v223
	v_and_b32_e32 v227, 0xffff0000, v223
	v_lshlrev_b32_e32 v224, 16, v222
	v_and_b32_e32 v225, 0xffff0000, v222
	v_and_b32_e32 v223, 0xffff0000, v221
	v_lshlrev_b32_e32 v222, 16, v221
	v_and_b32_e32 v221, 0xffff0000, v220
	v_lshlrev_b32_e32 v220, 16, v220
	v_pk_fma_f32 v[220:221], v[42:43], v[54:55], v[220:221] neg_lo:[1,0,0] neg_hi:[1,0,0]
	v_pk_fma_f32 v[222:223], v[42:43], v[56:57], v[222:223] neg_lo:[1,0,0] neg_hi:[1,0,0]
	v_pk_fma_f32 v[224:225], v[42:43], v[58:59], v[224:225] neg_lo:[1,0,0] neg_hi:[1,0,0]
	v_pk_fma_f32 v[226:227], v[42:43], v[60:61], v[226:227] neg_lo:[1,0,0] neg_hi:[1,0,0]
	v_mul_f32_e32 v54, v221, v221
	v_mul_f32_e32 v55, v223, v223
	v_mul_f32_e32 v56, v225, v225
	v_mul_f32_e32 v57, v227, v227
	v_fma_f32 v54, v220, v220, v54
	v_fma_f32 v55, v222, v222, v55
	v_fma_f32 v56, v224, v224, v56
	v_fma_f32 v57, v226, v226, v57
	v_add_f32_e32 v54, v54, v55
	v_add_f32_e32 v56, v56, v57
	v_add_f32_e32 v77, v54, v56
	ds_bpermute_b32 v78, v8, v62
	ds_bpermute_b32 v79, v8, v63
	ds_bpermute_b32 v80, v8, v64
	ds_bpermute_b32 v81, v8, v65
	ds_bpermute_b32 v82, v8, v66
	ds_bpermute_b32 v83, v8, v67
	ds_bpermute_b32 v84, v8, v68
	ds_bpermute_b32 v85, v8, v69
	s_waitcnt lgkmcnt(0)
	v_add_f32_e32 v62, v62, v78
	v_add_f32_e32 v63, v63, v79
	v_add_f32_e32 v64, v64, v80
	v_add_f32_e32 v65, v65, v81
	v_add_f32_e32 v66, v66, v82
	v_add_f32_e32 v67, v67, v83
	v_add_f32_e32 v68, v68, v84
	v_add_f32_e32 v69, v69, v85
	ds_bpermute_b32 v86, v8, v70
	ds_bpermute_b32 v87, v8, v71
	ds_bpermute_b32 v88, v8, v72
	ds_bpermute_b32 v89, v8, v73
	ds_bpermute_b32 v90, v8, v74
	ds_bpermute_b32 v91, v8, v75
	ds_bpermute_b32 v92, v8, v76
	ds_bpermute_b32 v93, v8, v77
	s_waitcnt lgkmcnt(0)
	v_add_f32_e32 v70, v70, v86
	v_add_f32_e32 v71, v71, v87
	v_add_f32_e32 v72, v72, v88
	v_add_f32_e32 v73, v73, v89
	v_add_f32_e32 v74, v74, v90
	v_add_f32_e32 v75, v75, v91
	v_add_f32_e32 v76, v76, v92
	v_add_f32_e32 v77, v77, v93
	ds_bpermute_b32 v78, v50, v62
	ds_bpermute_b32 v79, v50, v63
	ds_bpermute_b32 v80, v50, v64
	ds_bpermute_b32 v81, v50, v65
	ds_bpermute_b32 v82, v50, v66
	ds_bpermute_b32 v83, v50, v67
	ds_bpermute_b32 v84, v50, v68
	ds_bpermute_b32 v85, v50, v69
	s_waitcnt lgkmcnt(0)
	v_add_f32_e32 v62, v62, v78
	v_add_f32_e32 v63, v63, v79
	v_add_f32_e32 v64, v64, v80
	v_add_f32_e32 v65, v65, v81
	v_add_f32_e32 v66, v66, v82
	v_add_f32_e32 v67, v67, v83
	v_add_f32_e32 v68, v68, v84
	v_add_f32_e32 v69, v69, v85
	ds_bpermute_b32 v86, v50, v70
	ds_bpermute_b32 v87, v50, v71
	ds_bpermute_b32 v88, v50, v72
	ds_bpermute_b32 v89, v50, v73
	ds_bpermute_b32 v90, v50, v74
	ds_bpermute_b32 v91, v50, v75
	ds_bpermute_b32 v92, v50, v76
	ds_bpermute_b32 v93, v50, v77
	s_waitcnt lgkmcnt(0)
	v_add_f32_e32 v70, v70, v86
	v_add_f32_e32 v71, v71, v87
	v_add_f32_e32 v72, v72, v88
	v_add_f32_e32 v73, v73, v89
	v_add_f32_e32 v74, v74, v90
	v_add_f32_e32 v75, v75, v91
	v_add_f32_e32 v76, v76, v92
	v_add_f32_e32 v77, v77, v93
	ds_bpermute_b32 v78, v51, v62
	ds_bpermute_b32 v79, v51, v63
	ds_bpermute_b32 v80, v51, v64
	ds_bpermute_b32 v81, v51, v65
	ds_bpermute_b32 v82, v51, v66
	ds_bpermute_b32 v83, v51, v67
	ds_bpermute_b32 v84, v51, v68
	ds_bpermute_b32 v85, v51, v69
	s_waitcnt lgkmcnt(0)
	v_add_f32_e32 v62, v62, v78
	v_add_f32_e32 v63, v63, v79
	v_add_f32_e32 v64, v64, v80
	v_add_f32_e32 v65, v65, v81
	v_add_f32_e32 v66, v66, v82
	v_add_f32_e32 v67, v67, v83
	v_add_f32_e32 v68, v68, v84
	v_add_f32_e32 v69, v69, v85
	ds_bpermute_b32 v86, v51, v70
	ds_bpermute_b32 v87, v51, v71
	ds_bpermute_b32 v88, v51, v72
	ds_bpermute_b32 v89, v51, v73
	ds_bpermute_b32 v90, v51, v74
	ds_bpermute_b32 v91, v51, v75
	ds_bpermute_b32 v92, v51, v76
	ds_bpermute_b32 v93, v51, v77
	s_waitcnt lgkmcnt(0)
	v_add_f32_e32 v70, v70, v86
	v_add_f32_e32 v71, v71, v87
	v_add_f32_e32 v72, v72, v88
	v_add_f32_e32 v73, v73, v89
	v_add_f32_e32 v74, v74, v90
	v_add_f32_e32 v75, v75, v91
	v_add_f32_e32 v76, v76, v92
	v_add_f32_e32 v77, v77, v93
	ds_bpermute_b32 v78, v52, v62
	ds_bpermute_b32 v79, v52, v63
	ds_bpermute_b32 v80, v52, v64
	ds_bpermute_b32 v81, v52, v65
	ds_bpermute_b32 v82, v52, v66
	ds_bpermute_b32 v83, v52, v67
	ds_bpermute_b32 v84, v52, v68
	ds_bpermute_b32 v85, v52, v69
	s_waitcnt lgkmcnt(0)
	v_add_f32_e32 v62, v62, v78
	v_add_f32_e32 v63, v63, v79
	v_add_f32_e32 v64, v64, v80
	v_add_f32_e32 v65, v65, v81
	v_add_f32_e32 v66, v66, v82
	v_add_f32_e32 v67, v67, v83
	v_add_f32_e32 v68, v68, v84
	v_add_f32_e32 v69, v69, v85
	ds_bpermute_b32 v86, v52, v70
	ds_bpermute_b32 v87, v52, v71
	ds_bpermute_b32 v88, v52, v72
	ds_bpermute_b32 v89, v52, v73
	ds_bpermute_b32 v90, v52, v74
	ds_bpermute_b32 v91, v52, v75
	ds_bpermute_b32 v92, v52, v76
	ds_bpermute_b32 v93, v52, v77
	s_waitcnt lgkmcnt(0)
	v_add_f32_e32 v70, v70, v86
	v_add_f32_e32 v71, v71, v87
	v_add_f32_e32 v72, v72, v88
	v_add_f32_e32 v73, v73, v89
	v_add_f32_e32 v74, v74, v90
	v_add_f32_e32 v75, v75, v91
	v_add_f32_e32 v76, v76, v92
	v_add_f32_e32 v77, v77, v93
	v_fmamk_f32 v62, v62, 0x3c000000, v247
	v_fmamk_f32 v63, v63, 0x3c000000, v247
	v_fmamk_f32 v64, v64, 0x3c000000, v247
	v_fmamk_f32 v65, v65, 0x3c000000, v247
	v_fmamk_f32 v66, v66, 0x3c000000, v247
	v_fmamk_f32 v67, v67, 0x3c000000, v247
	v_fmamk_f32 v68, v68, 0x3c000000, v247
	v_fmamk_f32 v69, v69, 0x3c000000, v247
	v_fmamk_f32 v70, v70, 0x3c000000, v247
	v_fmamk_f32 v71, v71, 0x3c000000, v247
	v_fmamk_f32 v72, v72, 0x3c000000, v247
	v_fmamk_f32 v73, v73, 0x3c000000, v247
	v_fmamk_f32 v74, v74, 0x3c000000, v247
	v_fmamk_f32 v75, v75, 0x3c000000, v247
	v_fmamk_f32 v76, v76, 0x3c000000, v247
	v_fmamk_f32 v77, v77, 0x3c000000, v247
	v_rsq_f32_e32 v62, v62
	v_rsq_f32_e32 v63, v63
	v_rsq_f32_e32 v64, v64
	v_rsq_f32_e32 v65, v65
	v_rsq_f32_e32 v66, v66
	v_rsq_f32_e32 v67, v67
	v_rsq_f32_e32 v68, v68
	v_rsq_f32_e32 v69, v69
	v_rsq_f32_e32 v70, v70
	v_rsq_f32_e32 v71, v71
	v_rsq_f32_e32 v72, v72
	v_rsq_f32_e32 v73, v73
	v_rsq_f32_e32 v74, v74
	v_rsq_f32_e32 v75, v75
	v_rsq_f32_e32 v76, v76
	v_rsq_f32_e32 v77, v77
	v_mul_f32_e32 v78, v53, v62
	v_mul_f32_e32 v79, v53, v63
	v_mul_f32_e32 v80, v53, v64
	v_mul_f32_e32 v81, v53, v65
	v_mul_f32_e32 v82, v53, v66
	v_mul_f32_e32 v83, v53, v67
	v_mul_f32_e32 v84, v53, v68
	v_mul_f32_e32 v85, v53, v69
	v_mul_f32_e32 v86, v53, v70
	v_mul_f32_e32 v87, v53, v71
	v_mul_f32_e32 v88, v53, v72
	v_mul_f32_e32 v89, v53, v73
	v_mul_f32_e32 v90, v53, v74
	v_mul_f32_e32 v91, v53, v75
	v_mul_f32_e32 v92, v53, v76
	v_mul_f32_e32 v93, v53, v77
	v_pk_mul_f32 v[100:101], v[0:1], v[100:101]
	v_pk_mul_f32 v[102:103], v[2:3], v[102:103]
	v_pk_mul_f32 v[104:105], v[4:5], v[104:105]
	v_pk_mul_f32 v[106:107], v[6:7], v[106:107]
	v_pk_mul_f32 v[100:101], v[100:101], v[78:79] op_sel_hi:[1,0]
	v_pk_mul_f32 v[102:103], v[102:103], v[78:79] op_sel_hi:[1,0]
	v_pk_mul_f32 v[104:105], v[104:105], v[78:79] op_sel_hi:[1,0]
	v_pk_mul_f32 v[106:107], v[106:107], v[78:79] op_sel_hi:[1,0]
	v_cvt_pk_bf16_f32 v100, v100, v101
	v_cvt_pk_bf16_f32 v101, v102, v103
	v_cvt_pk_bf16_f32 v102, v104, v105
	v_cvt_pk_bf16_f32 v103, v106, v107
	global_store_dwordx4 v13, v[100:103], s[14:15]
	s_add_u32 s14, s14, 0x800
	s_addc_u32 s15, s15, 0
	v_mov_b32_e32 v54, v79
	v_pk_mul_f32 v[108:109], v[0:1], v[108:109]
	v_pk_mul_f32 v[110:111], v[2:3], v[110:111]
	v_pk_mul_f32 v[112:113], v[4:5], v[112:113]
	v_pk_mul_f32 v[114:115], v[6:7], v[114:115]
	v_pk_mul_f32 v[108:109], v[108:109], v[54:55] op_sel_hi:[1,0]
	v_pk_mul_f32 v[110:111], v[110:111], v[54:55] op_sel_hi:[1,0]
	v_pk_mul_f32 v[112:113], v[112:113], v[54:55] op_sel_hi:[1,0]
	v_pk_mul_f32 v[114:115], v[114:115], v[54:55] op_sel_hi:[1,0]
	v_cvt_pk_bf16_f32 v108, v108, v109
	v_cvt_pk_bf16_f32 v109, v110, v111
	v_cvt_pk_bf16_f32 v110, v112, v113
	v_cvt_pk_bf16_f32 v111, v114, v115
	global_store_dwordx4 v13, v[108:111], s[14:15]
	s_add_u32 s14, s14, 0x800
	s_addc_u32 s15, s15, 0
	v_pk_mul_f32 v[116:117], v[0:1], v[116:117]
	v_pk_mul_f32 v[118:119], v[2:3], v[118:119]
	v_pk_mul_f32 v[120:121], v[4:5], v[120:121]
	v_pk_mul_f32 v[122:123], v[6:7], v[122:123]
	v_pk_mul_f32 v[116:117], v[116:117], v[80:81] op_sel_hi:[1,0]
	v_pk_mul_f32 v[118:119], v[118:119], v[80:81] op_sel_hi:[1,0]
	v_pk_mul_f32 v[120:121], v[120:121], v[80:81] op_sel_hi:[1,0]
	v_pk_mul_f32 v[122:123], v[122:123], v[80:81] op_sel_hi:[1,0]
	v_cvt_pk_bf16_f32 v116, v116, v117
	v_cvt_pk_bf16_f32 v117, v118, v119
	v_cvt_pk_bf16_f32 v118, v120, v121
	v_cvt_pk_bf16_f32 v119, v122, v123
	global_store_dwordx4 v13, v[116:119], s[14:15]
	s_add_u32 s14, s14, 0x800
	s_addc_u32 s15, s15, 0
	v_mov_b32_e32 v54, v81
	v_pk_mul_f32 v[124:125], v[0:1], v[124:125]
	v_pk_mul_f32 v[126:127], v[2:3], v[126:127]
	v_pk_mul_f32 v[128:129], v[4:5], v[128:129]
	v_pk_mul_f32 v[130:131], v[6:7], v[130:131]
	v_pk_mul_f32 v[124:125], v[124:125], v[54:55] op_sel_hi:[1,0]
	v_pk_mul_f32 v[126:127], v[126:127], v[54:55] op_sel_hi:[1,0]
	v_pk_mul_f32 v[128:129], v[128:129], v[54:55] op_sel_hi:[1,0]
	v_pk_mul_f32 v[130:131], v[130:131], v[54:55] op_sel_hi:[1,0]
	v_cvt_pk_bf16_f32 v124, v124, v125
	v_cvt_pk_bf16_f32 v125, v126, v127
	v_cvt_pk_bf16_f32 v126, v128, v129
	v_cvt_pk_bf16_f32 v127, v130, v131
	global_store_dwordx4 v13, v[124:127], s[14:15]
	s_add_u32 s14, s14, 0x800
	s_addc_u32 s15, s15, 0
	v_pk_mul_f32 v[132:133], v[0:1], v[132:133]
	v_pk_mul_f32 v[134:135], v[2:3], v[134:135]
	v_pk_mul_f32 v[136:137], v[4:5], v[136:137]
	v_pk_mul_f32 v[138:139], v[6:7], v[138:139]
	v_pk_mul_f32 v[132:133], v[132:133], v[82:83] op_sel_hi:[1,0]
	v_pk_mul_f32 v[134:135], v[134:135], v[82:83] op_sel_hi:[1,0]
	v_pk_mul_f32 v[136:137], v[136:137], v[82:83] op_sel_hi:[1,0]
	v_pk_mul_f32 v[138:139], v[138:139], v[82:83] op_sel_hi:[1,0]
	v_cvt_pk_bf16_f32 v132, v132, v133
	v_cvt_pk_bf16_f32 v133, v134, v135
	v_cvt_pk_bf16_f32 v134, v136, v137
	v_cvt_pk_bf16_f32 v135, v138, v139
	global_store_dwordx4 v13, v[132:135], s[14:15]
	s_add_u32 s14, s14, 0x800
	s_addc_u32 s15, s15, 0
	v_mov_b32_e32 v54, v83
	v_pk_mul_f32 v[140:141], v[0:1], v[140:141]
	v_pk_mul_f32 v[142:143], v[2:3], v[142:143]
	v_pk_mul_f32 v[144:145], v[4:5], v[144:145]
	v_pk_mul_f32 v[146:147], v[6:7], v[146:147]
	v_pk_mul_f32 v[140:141], v[140:141], v[54:55] op_sel_hi:[1,0]
	v_pk_mul_f32 v[142:143], v[142:143], v[54:55] op_sel_hi:[1,0]
	v_pk_mul_f32 v[144:145], v[144:145], v[54:55] op_sel_hi:[1,0]
	v_pk_mul_f32 v[146:147], v[146:147], v[54:55] op_sel_hi:[1,0]
	v_cvt_pk_bf16_f32 v140, v140, v141
	v_cvt_pk_bf16_f32 v141, v142, v143
	v_cvt_pk_bf16_f32 v142, v144, v145
	v_cvt_pk_bf16_f32 v143, v146, v147
	global_store_dwordx4 v13, v[140:143], s[14:15]
	s_add_u32 s14, s14, 0x800
	s_addc_u32 s15, s15, 0
	v_pk_mul_f32 v[148:149], v[0:1], v[148:149]
	v_pk_mul_f32 v[150:151], v[2:3], v[150:151]
	v_pk_mul_f32 v[152:153], v[4:5], v[152:153]
	v_pk_mul_f32 v[154:155], v[6:7], v[154:155]
	v_pk_mul_f32 v[148:149], v[148:149], v[84:85] op_sel_hi:[1,0]
	v_pk_mul_f32 v[150:151], v[150:151], v[84:85] op_sel_hi:[1,0]
	v_pk_mul_f32 v[152:153], v[152:153], v[84:85] op_sel_hi:[1,0]
	v_pk_mul_f32 v[154:155], v[154:155], v[84:85] op_sel_hi:[1,0]
	v_cvt_pk_bf16_f32 v148, v148, v149
	v_cvt_pk_bf16_f32 v149, v150, v151
	v_cvt_pk_bf16_f32 v150, v152, v153
	v_cvt_pk_bf16_f32 v151, v154, v155
	global_store_dwordx4 v13, v[148:151], s[14:15]
	s_add_u32 s14, s14, 0x800
	s_addc_u32 s15, s15, 0
	v_mov_b32_e32 v54, v85
	v_pk_mul_f32 v[156:157], v[0:1], v[156:157]
	v_pk_mul_f32 v[158:159], v[2:3], v[158:159]
	v_pk_mul_f32 v[160:161], v[4:5], v[160:161]
	v_pk_mul_f32 v[162:163], v[6:7], v[162:163]
	v_pk_mul_f32 v[156:157], v[156:157], v[54:55] op_sel_hi:[1,0]
	v_pk_mul_f32 v[158:159], v[158:159], v[54:55] op_sel_hi:[1,0]
	v_pk_mul_f32 v[160:161], v[160:161], v[54:55] op_sel_hi:[1,0]
	v_pk_mul_f32 v[162:163], v[162:163], v[54:55] op_sel_hi:[1,0]
	v_cvt_pk_bf16_f32 v156, v156, v157
	v_cvt_pk_bf16_f32 v157, v158, v159
	v_cvt_pk_bf16_f32 v158, v160, v161
	v_cvt_pk_bf16_f32 v159, v162, v163
	global_store_dwordx4 v13, v[156:159], s[14:15]
	s_add_u32 s14, s14, 0x800
	s_addc_u32 s15, s15, 0
	v_pk_mul_f32 v[164:165], v[0:1], v[164:165]
	v_pk_mul_f32 v[166:167], v[2:3], v[166:167]
	v_pk_mul_f32 v[168:169], v[4:5], v[168:169]
	v_pk_mul_f32 v[170:171], v[6:7], v[170:171]
	v_pk_mul_f32 v[164:165], v[164:165], v[86:87] op_sel_hi:[1,0]
	v_pk_mul_f32 v[166:167], v[166:167], v[86:87] op_sel_hi:[1,0]
	v_pk_mul_f32 v[168:169], v[168:169], v[86:87] op_sel_hi:[1,0]
	v_pk_mul_f32 v[170:171], v[170:171], v[86:87] op_sel_hi:[1,0]
	v_cvt_pk_bf16_f32 v164, v164, v165
	v_cvt_pk_bf16_f32 v165, v166, v167
	v_cvt_pk_bf16_f32 v166, v168, v169
	v_cvt_pk_bf16_f32 v167, v170, v171
	global_store_dwordx4 v13, v[164:167], s[14:15]
	s_add_u32 s14, s14, 0x800
	s_addc_u32 s15, s15, 0
	v_mov_b32_e32 v54, v87
	v_pk_mul_f32 v[172:173], v[0:1], v[172:173]
	v_pk_mul_f32 v[174:175], v[2:3], v[174:175]
	v_pk_mul_f32 v[176:177], v[4:5], v[176:177]
	v_pk_mul_f32 v[178:179], v[6:7], v[178:179]
	v_pk_mul_f32 v[172:173], v[172:173], v[54:55] op_sel_hi:[1,0]
	v_pk_mul_f32 v[174:175], v[174:175], v[54:55] op_sel_hi:[1,0]
	v_pk_mul_f32 v[176:177], v[176:177], v[54:55] op_sel_hi:[1,0]
	v_pk_mul_f32 v[178:179], v[178:179], v[54:55] op_sel_hi:[1,0]
	v_cvt_pk_bf16_f32 v172, v172, v173
	v_cvt_pk_bf16_f32 v173, v174, v175
	v_cvt_pk_bf16_f32 v174, v176, v177
	v_cvt_pk_bf16_f32 v175, v178, v179
	global_store_dwordx4 v13, v[172:175], s[14:15]
	s_add_u32 s14, s14, 0x800
	s_addc_u32 s15, s15, 0
	v_pk_mul_f32 v[180:181], v[0:1], v[180:181]
	v_pk_mul_f32 v[182:183], v[2:3], v[182:183]
	v_pk_mul_f32 v[184:185], v[4:5], v[184:185]
	v_pk_mul_f32 v[186:187], v[6:7], v[186:187]
	v_pk_mul_f32 v[180:181], v[180:181], v[88:89] op_sel_hi:[1,0]
	v_pk_mul_f32 v[182:183], v[182:183], v[88:89] op_sel_hi:[1,0]
	v_pk_mul_f32 v[184:185], v[184:185], v[88:89] op_sel_hi:[1,0]
	v_pk_mul_f32 v[186:187], v[186:187], v[88:89] op_sel_hi:[1,0]
	v_cvt_pk_bf16_f32 v180, v180, v181
	v_cvt_pk_bf16_f32 v181, v182, v183
	v_cvt_pk_bf16_f32 v182, v184, v185
	v_cvt_pk_bf16_f32 v183, v186, v187
	global_store_dwordx4 v13, v[180:183], s[14:15]
	s_add_u32 s14, s14, 0x800
	s_addc_u32 s15, s15, 0
	v_mov_b32_e32 v54, v89
	v_pk_mul_f32 v[188:189], v[0:1], v[188:189]
	v_pk_mul_f32 v[190:191], v[2:3], v[190:191]
	v_pk_mul_f32 v[192:193], v[4:5], v[192:193]
	v_pk_mul_f32 v[194:195], v[6:7], v[194:195]
	v_pk_mul_f32 v[188:189], v[188:189], v[54:55] op_sel_hi:[1,0]
	v_pk_mul_f32 v[190:191], v[190:191], v[54:55] op_sel_hi:[1,0]
	v_pk_mul_f32 v[192:193], v[192:193], v[54:55] op_sel_hi:[1,0]
	v_pk_mul_f32 v[194:195], v[194:195], v[54:55] op_sel_hi:[1,0]
	v_cvt_pk_bf16_f32 v188, v188, v189
	v_cvt_pk_bf16_f32 v189, v190, v191
	v_cvt_pk_bf16_f32 v190, v192, v193
	v_cvt_pk_bf16_f32 v191, v194, v195
	global_store_dwordx4 v13, v[188:191], s[14:15]
	s_add_u32 s14, s14, 0x800
	s_addc_u32 s15, s15, 0
	v_pk_mul_f32 v[196:197], v[0:1], v[196:197]
	v_pk_mul_f32 v[198:199], v[2:3], v[198:199]
	v_pk_mul_f32 v[200:201], v[4:5], v[200:201]
	v_pk_mul_f32 v[202:203], v[6:7], v[202:203]
	v_pk_mul_f32 v[196:197], v[196:197], v[90:91] op_sel_hi:[1,0]
	v_pk_mul_f32 v[198:199], v[198:199], v[90:91] op_sel_hi:[1,0]
	v_pk_mul_f32 v[200:201], v[200:201], v[90:91] op_sel_hi:[1,0]
	v_pk_mul_f32 v[202:203], v[202:203], v[90:91] op_sel_hi:[1,0]
	v_cvt_pk_bf16_f32 v196, v196, v197
	v_cvt_pk_bf16_f32 v197, v198, v199
	v_cvt_pk_bf16_f32 v198, v200, v201
	v_cvt_pk_bf16_f32 v199, v202, v203
	global_store_dwordx4 v13, v[196:199], s[14:15]
	s_add_u32 s14, s14, 0x800
	s_addc_u32 s15, s15, 0
	v_mov_b32_e32 v54, v91
	v_pk_mul_f32 v[204:205], v[0:1], v[204:205]
	v_pk_mul_f32 v[206:207], v[2:3], v[206:207]
	v_pk_mul_f32 v[208:209], v[4:5], v[208:209]
	v_pk_mul_f32 v[210:211], v[6:7], v[210:211]
	v_pk_mul_f32 v[204:205], v[204:205], v[54:55] op_sel_hi:[1,0]
	v_pk_mul_f32 v[206:207], v[206:207], v[54:55] op_sel_hi:[1,0]
	v_pk_mul_f32 v[208:209], v[208:209], v[54:55] op_sel_hi:[1,0]
	v_pk_mul_f32 v[210:211], v[210:211], v[54:55] op_sel_hi:[1,0]
	v_cvt_pk_bf16_f32 v204, v204, v205
	v_cvt_pk_bf16_f32 v205, v206, v207
	v_cvt_pk_bf16_f32 v206, v208, v209
	v_cvt_pk_bf16_f32 v207, v210, v211
	global_store_dwordx4 v13, v[204:207], s[14:15]
	s_add_u32 s14, s14, 0x800
	s_addc_u32 s15, s15, 0
	v_pk_mul_f32 v[212:213], v[0:1], v[212:213]
	v_pk_mul_f32 v[214:215], v[2:3], v[214:215]
	v_pk_mul_f32 v[216:217], v[4:5], v[216:217]
	v_pk_mul_f32 v[218:219], v[6:7], v[218:219]
	v_pk_mul_f32 v[212:213], v[212:213], v[92:93] op_sel_hi:[1,0]
	v_pk_mul_f32 v[214:215], v[214:215], v[92:93] op_sel_hi:[1,0]
	v_pk_mul_f32 v[216:217], v[216:217], v[92:93] op_sel_hi:[1,0]
	v_pk_mul_f32 v[218:219], v[218:219], v[92:93] op_sel_hi:[1,0]
	v_cvt_pk_bf16_f32 v212, v212, v213
	v_cvt_pk_bf16_f32 v213, v214, v215
	v_cvt_pk_bf16_f32 v214, v216, v217
	v_cvt_pk_bf16_f32 v215, v218, v219
	global_store_dwordx4 v13, v[212:215], s[14:15]
	s_add_u32 s14, s14, 0x800
	s_addc_u32 s15, s15, 0
	v_mov_b32_e32 v54, v93
	v_pk_mul_f32 v[220:221], v[0:1], v[220:221]
	v_pk_mul_f32 v[222:223], v[2:3], v[222:223]
	v_pk_mul_f32 v[224:225], v[4:5], v[224:225]
	v_pk_mul_f32 v[226:227], v[6:7], v[226:227]
	v_pk_mul_f32 v[220:221], v[220:221], v[54:55] op_sel_hi:[1,0]
	v_pk_mul_f32 v[222:223], v[222:223], v[54:55] op_sel_hi:[1,0]
	v_pk_mul_f32 v[224:225], v[224:225], v[54:55] op_sel_hi:[1,0]
	v_pk_mul_f32 v[226:227], v[226:227], v[54:55] op_sel_hi:[1,0]
	v_cvt_pk_bf16_f32 v220, v220, v221
	v_cvt_pk_bf16_f32 v221, v222, v223
	v_cvt_pk_bf16_f32 v222, v224, v225
	v_cvt_pk_bf16_f32 v223, v226, v227
	global_store_dwordx4 v13, v[220:223], s[14:15]
